# P0 rmsnorm row sum: the 4 intra-row butterfly steps use DPP adds (quad_perm / row_half_mirror / row_mirror) instead of ds_bpermute round trips
# baseline (speedup 1.0000x reference)
; DI void rmsnorm_rows(const float* src, const float* w, u16* dst, const float* wabT, float* ab, int bid, int nb) {
;     ...
;     const float4* xr = (const float4*)(src + (size_t)row * 1024);
;     float4 v[4]; float ss = 0.f;
; #pragma unroll
;     for (int i = 0; i < 4; i++) { v[i] = xr[lane + 64 * i]; ss += v[i].x * v[i].x + v[i].y * v[i].y + v[i].z * v[i].z + v[i].w * v[i].w; }
;     ss = wsum(ss);
;     const float rstd = rsqrtf(ss * (1.f / 1024.f) + EPSF);
;     float acc[8];
; #pragma unroll
;     for (int j = 0; j < 8; j++) acc[j] = 0.f;
; #pragma unroll
;     for (int i = 0; i < 4; i++) {
;       const int k0 = (lane + 64 * i) * 4;
;       float4 ww = *(const float4*)(w + k0);
;       float y0 = v[i].x * rstd * ww.x, y1 = v[i].y * rstd * ww.y, y2 = v[i].z * rstd * ww.z, y3 = v[i].w * rstd * ww.w;
;       u32x2 pk; pk.x = pack2(y0, y1); pk.y = pack2(y2, y3);
;       *(u32x2*)(dst + (size_t)row * 1024 + k0) = pk;
;       if (wabT) {
; #pragma unroll
;         for (int j = 0; j < 8; j++) {
;           float4 wj = *(const float4*)(wabT + j * 1024 + k0);
;           acc[j] += y0 * wj.x + y1 * wj.y + y2 * wj.z + y3 * wj.w;
;         }
;       }
.LBB0_20:
	s_waitcnt vmcnt(4)
	v_add_u32_e32 v134, s8, v26
	v_lshl_add_u64 v[132:133], v[32:33], 0, s[10:11]
	v_cmp_gt_i32_e32 vcc, 0x4000, v134
	s_nop 0
	v_cndmask_b32_e32 v132, v32, v132, vcc
	v_cndmask_b32_e32 v133, v33, v133, vcc
	v_mov_b32_e32 v20, v116
	v_mov_b32_e32 v21, v117
	v_mov_b32_e32 v22, v118
	v_mov_b32_e32 v23, v119
	global_load_dwordx4 v[116:119], v[132:133], off offset:-1024
	s_waitcnt lgkmcnt(0)
	v_mov_b32_e32 v16, v120
	v_mov_b32_e32 v17, v121
	v_mov_b32_e32 v18, v122
	v_mov_b32_e32 v19, v123
	global_load_dwordx4 v[120:123], v[132:133], off
	v_mov_b32_e32 v12, v124
	v_mov_b32_e32 v13, v125
	v_mov_b32_e32 v14, v126
	v_mov_b32_e32 v15, v127
	global_load_dwordx4 v[124:127], v[132:133], off offset:1024
	s_mov_b32 s3, 0x800000
	v_mov_b32_e32 v51, v21
	v_mov_b32_e32 v6, v17
	v_mov_b32_e32 v7, v13
	v_mov_b32_e32 v4, v16
	v_mov_b32_e32 v5, v12
	v_pk_mul_f32 v[6:7], v[6:7], v[6:7]
	v_mov_b32_e32 v49, v20
	v_pk_fma_f32 v[4:5], v[4:5], v[4:5], v[6:7]
	v_mov_b32_e32 v6, v18
	v_mov_b32_e32 v7, v14
	v_pk_fma_f32 v[4:5], v[6:7], v[6:7], v[4:5]
	v_mov_b32_e32 v6, v19
	v_mov_b32_e32 v7, v15
	v_pk_fma_f32 v[38:39], v[6:7], v[6:7], v[4:5]
	v_mov_b32_e32 v4, v128
	v_mov_b32_e32 v5, v129
	v_mov_b32_e32 v6, v130
	v_mov_b32_e32 v7, v131
	global_load_dwordx4 v[128:131], v[132:133], off offset:-2048
	v_mov_b32_e32 v8, v100
	v_mov_b32_e32 v9, v101
	v_mov_b32_e32 v10, v102
	v_mov_b32_e32 v11, v103
	v_mov_b32_e32 v45, v22
	v_mov_b32_e32 v47, v23
	v_mov_b32_e32 v50, v5
	v_mov_b32_e32 v48, v4
	v_pk_mul_f32 v[50:51], v[50:51], v[50:51]
	v_mov_b32_e32 v44, v6
	v_pk_fma_f32 v[48:49], v[48:49], v[48:49], v[50:51]
	v_mov_b32_e32 v46, v7
	v_pk_fma_f32 v[44:45], v[44:45], v[44:45], v[48:49]
	s_nop 0
	v_pk_fma_f32 v[44:45], v[46:47], v[46:47], v[44:45]
	s_nop 0
	v_add_f32_e32 v3, v44, v45
	v_add_f32_e32 v3, v3, v38
	v_add_f32_e32 v3, v3, v39
	ds_bpermute_b32 v29, v1, v3
	s_waitcnt lgkmcnt(0)
	v_add_f32_e32 v3, v3, v29
	ds_bpermute_b32 v29, v25, v3
	s_waitcnt lgkmcnt(0)
	v_add_f32_e32 v3, v3, v29
	s_nop 1
	v_add_f32_dpp v3, v3, v3 row_mirror row_mask:0xf bank_mask:0xf
	s_nop 1
	v_add_f32_dpp v3, v3, v3 row_half_mirror row_mask:0xf bank_mask:0xf
	s_nop 1
	v_add_f32_dpp v3, v3, v3 quad_perm:[2,3,0,1] row_mask:0xf bank_mask:0xf
	s_nop 1
	v_add_f32_dpp v3, v3, v3 quad_perm:[1,0,3,2] row_mask:0xf bank_mask:0xf
	v_fmamk_f32 v3, v3, 0x3a800000, v27
	v_cmp_gt_f32_e32 vcc, s3, v3
	v_mul_f32_e32 v29, 0x4b800000, v3
	s_nop 0
	v_cndmask_b32_e32 v3, v3, v29, vcc
	v_rsq_f32_e32 v3, v3
	s_nop 0
	v_mul_f32_e32 v29, 0x45800000, v3
	v_cndmask_b32_e32 v38, v3, v29, vcc
	v_pk_mul_f32 v[4:5], v[4:5], v[38:39] op_sel_hi:[1,0]
	v_pk_mul_f32 v[6:7], v[6:7], v[38:39] op_sel_hi:[1,0]
	v_pk_mul_f32 v[4:5], v[8:9], v[4:5]
	v_pk_mul_f32 v[6:7], v[10:11], v[6:7]
	v_cvt_pk_bf16_f32 v8, v4, v5
	v_cvt_pk_bf16_f32 v9, v6, v7
	s_and_b64 vcc, exec, s[4:5]
	global_store_dwordx2 v[36:37], v[8:9], off offset:-1024
	s_cbranch_vccnz .LBB0_22
	ds_read_b128 v[8:11], v28 offset:256
	ds_read_b128 v[44:47], v28 offset:4352
	ds_read_b128 v[48:51], v28 offset:8448
	ds_read_b128 v[52:55], v28 offset:12544
	s_waitcnt lgkmcnt(3)
	v_mov_b32_e32 v62, v10
	s_waitcnt lgkmcnt(2)
	v_pk_mov_b32 v[60:61], v[8:9], v[44:45] op_sel:[1,0]
	v_mov_b32_e32 v9, v45
	v_pk_mul_f32 v[44:45], v[4:5], v[8:9]
	v_mov_b32_e32 v63, v46
	v_mov_b32_e32 v46, v11
	ds_read_b128 v[8:11], v28 offset:16640
	ds_read_b128 v[56:59], v28 offset:20736
	s_waitcnt lgkmcnt(2)
	v_pk_mov_b32 v[64:65], v[48:49], v[52:53] op_sel:[1,0]
	v_mov_b32_e32 v49, v53
	v_pk_mul_f32 v[52:53], v[4:5], v[48:49]
	v_mov_b32_e32 v66, v50
	s_waitcnt lgkmcnt(0)
	v_pk_mov_b32 v[68:69], v[8:9], v[56:57] op_sel:[1,0]
	v_mov_b32_e32 v9, v57
	v_mov_b32_e32 v67, v54
	v_mov_b32_e32 v54, v51
	v_pk_mul_f32 v[56:57], v[4:5], v[8:9]
	ds_read_b128 v[48:51], v28 offset:24832
	v_mov_b32_e32 v70, v10
	v_mov_b32_e32 v71, v58
	v_mov_b32_e32 v58, v11
	ds_read_b128 v[8:11], v28 offset:28928
	s_waitcnt lgkmcnt(1)
	v_mul_f32_e32 v48, v4, v48
	v_mul_f32_e32 v72, v5, v49
	v_mul_f32_e32 v50, v6, v50
	v_mul_f32_e32 v74, v7, v51
	s_waitcnt lgkmcnt(0)
	v_pk_mul_f32 v[8:9], v[4:5], v[8:9]
	v_pk_mul_f32 v[10:11], v[6:7], v[10:11]
	v_mov_b32_e32 v49, v8
	v_mov_b32_e32 v73, v9
	v_mov_b32_e32 v51, v10
	v_mov_b32_e32 v75, v11
	v_pk_fma_f32 v[8:9], v[4:5], v[60:61], v[44:45] op_sel:[1,0,0] op_sel_hi:[0,1,1]
	v_pk_fma_f32 v[10:11], v[4:5], v[64:65], v[52:53] op_sel:[1,0,0] op_sel_hi:[0,1,1]
	v_pk_fma_f32 v[4:5], v[4:5], v[68:69], v[56:57] op_sel:[1,0,0] op_sel_hi:[0,1,1]
	v_pk_add_f32 v[44:45], v[48:49], v[72:73]
	v_pk_fma_f32 v[8:9], v[6:7], v[62:63], v[8:9] op_sel_hi:[0,1,1]
	v_pk_fma_f32 v[10:11], v[6:7], v[66:67], v[10:11] op_sel_hi:[0,1,1]
	v_pk_fma_f32 v[4:5], v[6:7], v[70:71], v[4:5] op_sel_hi:[0,1,1]
	v_pk_add_f32 v[44:45], v[44:45], v[50:51]
	v_pk_fma_f32 v[46:47], v[6:7], v[46:47], v[8:9] op_sel:[1,0,0]
	v_pk_fma_f32 v[10:11], v[6:7], v[54:55], v[10:11] op_sel:[1,0,0]
	v_pk_fma_f32 v[4:5], v[6:7], v[58:59], v[4:5] op_sel:[1,0,0]
	v_pk_add_f32 v[44:45], v[44:45], v[74:75]
	v_pk_add_f32 v[8:9], v[4:5], 0 op_sel_hi:[1,0]
	v_pk_add_f32 v[6:7], v[10:11], 0 op_sel_hi:[1,0]
	v_pk_add_f32 v[4:5], v[46:47], 0 op_sel_hi:[1,0]
	v_pk_add_f32 v[10:11], v[44:45], 0 op_sel_hi:[1,0]
	s_branch .LBB0_23
